# HGRN2 output pass: the 20 LDS operand reads of the inter-chunk product issued together (were 16 serialized round trips), MFMAs with counted waits
# speedup vs baseline: 1.0037x; 1.0036x over previous
.LBB0_197:
	ds_read_b128 v[10:13], v130 offset:17408
	ds_read_b128 v[166:169], v127
	ds_read_b128 v[170:173], v127 offset:4352
	ds_read_b128 v[174:177], v127 offset:8704
	ds_read_b128 v[178:181], v127 offset:13056
	ds_read_b128 v[182:185], v130 offset:17472
	ds_read_b128 v[186:189], v127 offset:64
	ds_read_b128 v[190:193], v127 offset:4416
	ds_read_b128 v[194:197], v127 offset:8768
	ds_read_b128 v[198:201], v127 offset:13120
	ds_read_b128 v[210:213], v130 offset:17536
	ds_read_b128 v[214:217], v127 offset:128
	ds_read_b128 v[218:221], v127 offset:4480
	ds_read_b128 v[222:225], v127 offset:8832
	ds_read_b128 v[226:229], v127 offset:13184
	ds_read_b128 v[230:233], v130 offset:17600
	ds_read_b128 v[234:237], v127 offset:192
	ds_read_b128 v[238:241], v127 offset:4544
	ds_read_b128 v[242:245], v127 offset:8896
	ds_read_b128 v[246:249], v127 offset:13248
	s_waitcnt lgkmcnt(15)
	v_mfma_f32_16x16x32_bf16 v[48:51], v[166:169], v[10:13], v[48:51]
	s_waitcnt lgkmcnt(15)
	v_mfma_f32_16x16x32_bf16 v[52:55], v[170:173], v[10:13], v[52:55]
	s_waitcnt lgkmcnt(15)
	v_mfma_f32_16x16x32_bf16 v[56:59], v[174:177], v[10:13], v[56:59]
	s_waitcnt lgkmcnt(15)
	v_mfma_f32_16x16x32_bf16 v[10:13], v[178:181], v[10:13], v[60:63]
	s_waitcnt lgkmcnt(13)
	v_mfma_f32_16x16x32_bf16 v[48:51], v[186:189], v[182:185], v[48:51]
	s_waitcnt lgkmcnt(12)
	v_mfma_f32_16x16x32_bf16 v[52:55], v[190:193], v[182:185], v[52:55]
	s_waitcnt lgkmcnt(11)
	v_mfma_f32_16x16x32_bf16 v[56:59], v[194:197], v[182:185], v[56:59]
	s_waitcnt lgkmcnt(10)
	v_mfma_f32_16x16x32_bf16 v[10:13], v[198:201], v[182:185], v[10:13]
	s_waitcnt lgkmcnt(8)
	v_mfma_f32_16x16x32_bf16 v[48:51], v[214:217], v[210:213], v[48:51]
	s_waitcnt lgkmcnt(7)
	v_mfma_f32_16x16x32_bf16 v[52:55], v[218:221], v[210:213], v[52:55]
	s_waitcnt lgkmcnt(6)
	v_mfma_f32_16x16x32_bf16 v[64:67], v[222:225], v[210:213], v[56:59]
	s_waitcnt lgkmcnt(5)
	v_mfma_f32_16x16x32_bf16 v[10:13], v[226:229], v[210:213], v[10:13]
	s_waitcnt lgkmcnt(3)
	v_mfma_f32_16x16x32_bf16 v[56:59], v[234:237], v[230:233], v[48:51]
	s_waitcnt lgkmcnt(2)
	v_mfma_f32_16x16x32_bf16 v[52:55], v[238:241], v[230:233], v[52:55]
	s_waitcnt lgkmcnt(1)
	v_mfma_f32_16x16x32_bf16 v[48:51], v[242:245], v[230:233], v[64:67]
	s_waitcnt lgkmcnt(0)
	v_mfma_f32_16x16x32_bf16 v[10:13], v[246:249], v[230:233], v[10:13]
	s_nop 7
	v_mul_f32_e32 v14, v57, v57
	v_mul_f32_e32 v15, v59, v59
	v_fmac_f32_e32 v14, v56, v56
	v_fmac_f32_e32 v15, v58, v58
	v_add_f32_e32 v14, v14, v15
	v_mul_f32_e32 v15, v53, v53
	v_mul_f32_e32 v60, v55, v55
	v_fmac_f32_e32 v15, v52, v52
	v_fmac_f32_e32 v60, v54, v54
	v_add_f32_e32 v15, v15, v60
	v_add_f32_e32 v14, v14, v15
	v_mul_f32_e32 v15, v49, v49
	v_mul_f32_e32 v60, v51, v51
	v_fmac_f32_e32 v15, v48, v48
	v_fmac_f32_e32 v60, v50, v50
	v_add_f32_e32 v15, v15, v60
	v_add_f32_e32 v14, v14, v15
	v_mul_f32_e32 v15, v11, v11
	v_mul_f32_e32 v60, v13, v13
	v_fmac_f32_e32 v15, v10, v10
	v_fmac_f32_e32 v60, v12, v12
	v_add_f32_e32 v15, v15, v60
	v_add_f32_e32 v14, v14, v15
	ds_bpermute_b32 v15, v119, v14
	s_waitcnt lgkmcnt(0)
	v_add_f32_e32 v14, v14, v15
	ds_bpermute_b32 v15, v120, v14
	s_waitcnt lgkmcnt(0)
	v_add_f32_e32 v14, v14, v15
	s_and_saveexec_b64 s[36:37], s[10:11]
	s_cbranch_execz .LBB0_116
	ds_write_b32 v128, v14
	s_branch .LBB0_116
